# c24 + MLA fast path: the 20 copy-subs issued before the first PV MFMA packed as 10 v_pk_add_f32 (exposed region, no MFMA in flight)
# speedup vs baseline: 1.0113x; 1.0067x over previous
.Lfm_odd_exp:
	v_pk_add_f32 v[96:97], v[112:113], v[236:237] op_sel_hi:[1,0] neg_lo:[0,1] neg_hi:[0,1]
	ds_read_b64_tr_b16 v[112:113], v0 offset:0x200
	v_pk_add_f32 v[98:99], v[114:115], v[236:237] op_sel_hi:[1,0] neg_lo:[0,1] neg_hi:[0,1]
	ds_read_b64_tr_b16 v[114:115], v0 offset:0xa00
	v_pk_add_f32 v[100:101], v[116:117], v[236:237] op_sel_hi:[1,0] neg_lo:[0,1] neg_hi:[0,1]
	ds_read_b64_tr_b16 v[116:117], v0 offset:0x1200
	v_pk_add_f32 v[102:103], v[118:119], v[236:237] op_sel_hi:[1,0] neg_lo:[0,1] neg_hi:[0,1]
	ds_read_b64_tr_b16 v[118:119], v0 offset:0x1a00
	v_pk_add_f32 v[104:105], v[120:121], v[236:237] op_sel_hi:[1,0] neg_lo:[0,1] neg_hi:[0,1]
	ds_read_b64_tr_b16 v[120:121], v0 offset:0x2200
	v_pk_add_f32 v[106:107], v[122:123], v[236:237] op_sel_hi:[1,0] neg_lo:[0,1] neg_hi:[0,1]
	ds_read_b64_tr_b16 v[122:123], v0 offset:0x2a00
	v_pk_add_f32 v[108:109], v[124:125], v[236:237] op_sel_hi:[1,0] neg_lo:[0,1] neg_hi:[0,1]
	ds_read_b64_tr_b16 v[124:125], v0 offset:0x3200
	v_pk_add_f32 v[110:111], v[126:127], v[236:237] op_sel_hi:[1,0] neg_lo:[0,1] neg_hi:[0,1]
	ds_read_b64_tr_b16 v[126:127], v0 offset:0x3a00
	v_pk_add_f32 v[80:81], v[128:129], v[236:237] op_sel_hi:[1,0] neg_lo:[0,1] neg_hi:[0,1]
	v_pk_add_f32 v[82:83], v[130:131], v[236:237] op_sel_hi:[1,0] neg_lo:[0,1] neg_hi:[0,1]
	s_waitcnt lgkmcnt(8)
	v_mfma_f32_32x32x16_bf16 v[64:79], v[192:195], v[208:211], v[64:79]
	v_exp_f32_e32 v96, v96
	v_exp_f32_e32 v80, v80
	v_sub_f32_e32 v84, v132, v236
	v_sub_f32_e32 v85, v133, v236
	v_sub_f32_e32 v86, v134, v236
	v_mfma_f32_32x32x16_bf16 v[64:79], v[10:13], v[204:207], v[64:79]
	v_exp_f32_e32 v97, v97
	v_exp_f32_e32 v81, v81
	v_sub_f32_e32 v87, v135, v236
	v_sub_f32_e32 v88, v136, v236
	v_sub_f32_e32 v89, v137, v236
	v_mfma_f32_32x32x16_bf16 v[64:79], v[6:9], v[200:203], v[64:79]
	v_exp_f32_e32 v98, v98
	v_exp_f32_e32 v82, v82
	v_sub_f32_e32 v90, v138, v236
	v_sub_f32_e32 v91, v139, v236
	v_sub_f32_e32 v92, v140, v236
	v_mfma_f32_32x32x16_bf16 v[64:79], v[2:5], v[196:199], v[64:79]
	v_exp_f32_e32 v99, v99
	v_exp_f32_e32 v83, v83
	v_sub_f32_e32 v93, v141, v236
	v_sub_f32_e32 v94, v142, v236
	v_sub_f32_e32 v95, v143, v236
	ds_read_b64_tr_b16 v[128:129], v0 offset:0x400
	ds_read_b64_tr_b16 v[130:131], v0 offset:0xc00
	ds_read_b64_tr_b16 v[132:133], v0 offset:0x1400
	ds_read_b64_tr_b16 v[134:135], v0 offset:0x1c00
	ds_read_b64_tr_b16 v[136:137], v0 offset:0x2400
	ds_read_b64_tr_b16 v[138:139], v0 offset:0x2c00
	ds_read_b64_tr_b16 v[140:141], v0 offset:0x3400
	ds_read_b64_tr_b16 v[142:143], v0 offset:0x3c00
	s_waitcnt lgkmcnt(8)
	v_mfma_f32_32x32x16_bf16 v[48:63], v[192:195], v[112:115], v[48:63]
	v_exp_f32_e32 v100, v100
	v_exp_f32_e32 v84, v84
	v_mfma_f32_32x32x16_bf16 v[48:63], v[10:13], v[116:119], v[48:63]
	v_exp_f32_e32 v101, v101
	v_exp_f32_e32 v85, v85
	v_mfma_f32_32x32x16_bf16 v[48:63], v[6:9], v[120:123], v[48:63]
	v_exp_f32_e32 v102, v102
	v_exp_f32_e32 v86, v86
	v_mfma_f32_32x32x16_bf16 v[48:63], v[2:5], v[124:127], v[48:63]
	v_exp_f32_e32 v103, v103
	v_exp_f32_e32 v87, v87
	ds_read_b64_tr_b16 v[112:113], v0 offset:0x600
	ds_read_b64_tr_b16 v[114:115], v0 offset:0xe00
	ds_read_b64_tr_b16 v[116:117], v0 offset:0x1600
	ds_read_b64_tr_b16 v[118:119], v0 offset:0x1e00
	ds_read_b64_tr_b16 v[120:121], v0 offset:0x2600
	ds_read_b64_tr_b16 v[122:123], v0 offset:0x2e00
	ds_read_b64_tr_b16 v[124:125], v0 offset:0x3600
	ds_read_b64_tr_b16 v[126:127], v0 offset:0x3e00
	s_waitcnt lgkmcnt(8)
	v_mfma_f32_32x32x16_bf16 v[32:47], v[192:195], v[128:131], v[32:47]
	v_exp_f32_e32 v104, v104
	v_exp_f32_e32 v88, v88
	v_mfma_f32_32x32x16_bf16 v[32:47], v[10:13], v[132:135], v[32:47]
	v_exp_f32_e32 v105, v105
	v_exp_f32_e32 v89, v89
	v_mfma_f32_32x32x16_bf16 v[32:47], v[6:9], v[136:139], v[32:47]
	v_exp_f32_e32 v106, v106
	v_exp_f32_e32 v90, v90
	v_mfma_f32_32x32x16_bf16 v[32:47], v[2:5], v[140:143], v[32:47]
	v_exp_f32_e32 v107, v107
	v_exp_f32_e32 v91, v91
	s_waitcnt lgkmcnt(0)
	v_mfma_f32_32x32x16_bf16 v[16:31], v[192:195], v[112:115], v[16:31]
	v_exp_f32_e32 v108, v108
	v_exp_f32_e32 v92, v92
	v_mfma_f32_32x32x16_bf16 v[16:31], v[10:13], v[116:119], v[16:31]
	v_exp_f32_e32 v109, v109
	v_exp_f32_e32 v93, v93
	v_mfma_f32_32x32x16_bf16 v[16:31], v[6:9], v[120:123], v[16:31]
	v_exp_f32_e32 v110, v110
	v_exp_f32_e32 v94, v94
	v_mfma_f32_32x32x16_bf16 v[16:31], v[2:5], v[124:127], v[16:31]
	v_exp_f32_e32 v111, v111
	v_exp_f32_e32 v95, v95
	v_cmp_gt_f32_e32 vcc, 1.0, v240
	s_cbranch_vccnz .Lresc_mla_odd_blk

.Lfm_even_exp:
	v_pk_add_f32 v[96:97], v[112:113], v[236:237] op_sel_hi:[1,0] neg_lo:[0,1] neg_hi:[0,1]
	ds_read_b64_tr_b16 v[112:113], v243 offset:0x200
	v_pk_add_f32 v[98:99], v[114:115], v[236:237] op_sel_hi:[1,0] neg_lo:[0,1] neg_hi:[0,1]
	ds_read_b64_tr_b16 v[114:115], v243 offset:0xa00
	v_pk_add_f32 v[100:101], v[116:117], v[236:237] op_sel_hi:[1,0] neg_lo:[0,1] neg_hi:[0,1]
	ds_read_b64_tr_b16 v[116:117], v243 offset:0x1200
	v_pk_add_f32 v[102:103], v[118:119], v[236:237] op_sel_hi:[1,0] neg_lo:[0,1] neg_hi:[0,1]
	ds_read_b64_tr_b16 v[118:119], v243 offset:0x1a00
	v_pk_add_f32 v[104:105], v[120:121], v[236:237] op_sel_hi:[1,0] neg_lo:[0,1] neg_hi:[0,1]
	ds_read_b64_tr_b16 v[120:121], v243 offset:0x2200
	v_pk_add_f32 v[106:107], v[122:123], v[236:237] op_sel_hi:[1,0] neg_lo:[0,1] neg_hi:[0,1]
	ds_read_b64_tr_b16 v[122:123], v243 offset:0x2a00
	v_pk_add_f32 v[108:109], v[124:125], v[236:237] op_sel_hi:[1,0] neg_lo:[0,1] neg_hi:[0,1]
	ds_read_b64_tr_b16 v[124:125], v243 offset:0x3200
	v_pk_add_f32 v[110:111], v[126:127], v[236:237] op_sel_hi:[1,0] neg_lo:[0,1] neg_hi:[0,1]
	ds_read_b64_tr_b16 v[126:127], v243 offset:0x3a00
	v_pk_add_f32 v[80:81], v[128:129], v[236:237] op_sel_hi:[1,0] neg_lo:[0,1] neg_hi:[0,1]
	v_pk_add_f32 v[82:83], v[130:131], v[236:237] op_sel_hi:[1,0] neg_lo:[0,1] neg_hi:[0,1]
	s_waitcnt lgkmcnt(8)
	v_mfma_f32_32x32x16_bf16 v[64:79], v[192:195], v[208:211], v[64:79]
	v_exp_f32_e32 v96, v96
	v_exp_f32_e32 v80, v80
	v_sub_f32_e32 v84, v132, v236
	v_sub_f32_e32 v85, v133, v236
	v_sub_f32_e32 v86, v134, v236
	v_mfma_f32_32x32x16_bf16 v[64:79], v[10:13], v[204:207], v[64:79]
	v_exp_f32_e32 v97, v97
	v_exp_f32_e32 v81, v81
	v_sub_f32_e32 v87, v135, v236
	v_sub_f32_e32 v88, v136, v236
	v_sub_f32_e32 v89, v137, v236
	v_mfma_f32_32x32x16_bf16 v[64:79], v[6:9], v[200:203], v[64:79]
	v_exp_f32_e32 v98, v98
	v_exp_f32_e32 v82, v82
	v_sub_f32_e32 v90, v138, v236
	v_sub_f32_e32 v91, v139, v236
	v_sub_f32_e32 v92, v140, v236
	v_mfma_f32_32x32x16_bf16 v[64:79], v[2:5], v[196:199], v[64:79]
	v_exp_f32_e32 v99, v99
	v_exp_f32_e32 v83, v83
	v_sub_f32_e32 v93, v141, v236
	v_sub_f32_e32 v94, v142, v236
	v_sub_f32_e32 v95, v143, v236
	ds_read_b64_tr_b16 v[128:129], v243 offset:0x400
	ds_read_b64_tr_b16 v[130:131], v243 offset:0xc00
	ds_read_b64_tr_b16 v[132:133], v243 offset:0x1400
	ds_read_b64_tr_b16 v[134:135], v243 offset:0x1c00
	ds_read_b64_tr_b16 v[136:137], v243 offset:0x2400
	ds_read_b64_tr_b16 v[138:139], v243 offset:0x2c00
	ds_read_b64_tr_b16 v[140:141], v243 offset:0x3400
	ds_read_b64_tr_b16 v[142:143], v243 offset:0x3c00
	s_waitcnt lgkmcnt(8)
	v_mfma_f32_32x32x16_bf16 v[48:63], v[192:195], v[112:115], v[48:63]
	v_exp_f32_e32 v100, v100
	v_exp_f32_e32 v84, v84
	v_mfma_f32_32x32x16_bf16 v[48:63], v[10:13], v[116:119], v[48:63]
	v_exp_f32_e32 v101, v101
	v_exp_f32_e32 v85, v85
	v_mfma_f32_32x32x16_bf16 v[48:63], v[6:9], v[120:123], v[48:63]
	v_exp_f32_e32 v102, v102
	v_exp_f32_e32 v86, v86
	v_mfma_f32_32x32x16_bf16 v[48:63], v[2:5], v[124:127], v[48:63]
	v_exp_f32_e32 v103, v103
	v_exp_f32_e32 v87, v87
	ds_read_b64_tr_b16 v[112:113], v243 offset:0x600
	ds_read_b64_tr_b16 v[114:115], v243 offset:0xe00
	ds_read_b64_tr_b16 v[116:117], v243 offset:0x1600
	ds_read_b64_tr_b16 v[118:119], v243 offset:0x1e00
	ds_read_b64_tr_b16 v[120:121], v243 offset:0x2600
	ds_read_b64_tr_b16 v[122:123], v243 offset:0x2e00
	ds_read_b64_tr_b16 v[124:125], v243 offset:0x3600
	ds_read_b64_tr_b16 v[126:127], v243 offset:0x3e00
	s_waitcnt lgkmcnt(8)
	v_mfma_f32_32x32x16_bf16 v[32:47], v[192:195], v[128:131], v[32:47]
	v_exp_f32_e32 v104, v104
	v_exp_f32_e32 v88, v88
	v_mfma_f32_32x32x16_bf16 v[32:47], v[10:13], v[132:135], v[32:47]
	v_exp_f32_e32 v105, v105
	v_exp_f32_e32 v89, v89
	v_mfma_f32_32x32x16_bf16 v[32:47], v[6:9], v[136:139], v[32:47]
	v_exp_f32_e32 v106, v106
	v_exp_f32_e32 v90, v90
	v_mfma_f32_32x32x16_bf16 v[32:47], v[2:5], v[140:143], v[32:47]
	v_exp_f32_e32 v107, v107
	v_exp_f32_e32 v91, v91
	s_waitcnt lgkmcnt(0)
	v_mfma_f32_32x32x16_bf16 v[16:31], v[192:195], v[112:115], v[16:31]
	v_exp_f32_e32 v108, v108
	v_exp_f32_e32 v92, v92
	v_mfma_f32_32x32x16_bf16 v[16:31], v[10:13], v[116:119], v[16:31]
	v_exp_f32_e32 v109, v109
	v_exp_f32_e32 v93, v93
	v_mfma_f32_32x32x16_bf16 v[16:31], v[6:9], v[120:123], v[16:31]
	v_exp_f32_e32 v110, v110
	v_exp_f32_e32 v94, v94
	v_mfma_f32_32x32x16_bf16 v[16:31], v[2:5], v[124:127], v[16:31]
	v_exp_f32_e32 v111, v111
	v_exp_f32_e32 v95, v95
	v_cmp_gt_f32_e32 vcc, 1.0, v0
	s_cbranch_vccnz .Lresc_mla_even_blk
